# SSD conv5+SiLU phase hand-rewritten: weights kept in registers, all five tap rows loaded together, next item prefetched (de-serialised load latencies)
# speedup vs baseline: 1.0444x; 1.0062x over previous
; DI int get_tid() { int t = threadIdx.x; asm volatile("" : "+v"(t)); return t; }
; DI int get_bid() { int t = blockIdx.x; asm volatile("" : "+s"(t)); return t; }
; DI U4 pack8(const float (&x)[8]) { return mku4(pack2(x[0], x[1]), pack2(x[2], x[3]), pack2(x[4], x[5]), pack2(x[6], x[7])); }
; DI float siluf(float x) { return x / (1.f + __expf(-x)); }
; DI void ssd_conv8(const u16* zx, int row, int lo, int hi, int ch0, const float* cw, const float* cb, float (&out)[8]) {
;   F4 b0 = *(const F4*)(cb + ch0), b1 = *(const F4*)(cb + ch0 + 4);
;   float acc[8] = {b0.x, b0.y, b0.z, b0.w, b1.x, b1.y, b1.z, b1.w};
; #pragma unroll
;   for (int k = 0; k < 5; ++k) {
;     int rr = row + k - 2;
;     if (rr >= lo && rr < hi) {
;       U4 v = *(const U4*)(zx + (size_t)rr * 1536 + 512 + ch0); float x[8]; unpack8(v, x);
;       F4 w0 = *(const F4*)(cw + k * 1024 + ch0), w1 = *(const F4*)(cw + k * 1024 + ch0 + 4);
;       acc[0] += w0.x * x[0]; acc[1] += w0.y * x[1]; acc[2] += w0.z * x[2]; acc[3] += w0.w * x[3];
;       acc[4] += w1.x * x[4]; acc[5] += w1.y * x[5]; acc[6] += w1.z * x[6]; acc[7] += w1.w * x[7];
;     }
;   }
; #pragma unroll
;   for (int e = 0; e < 8; ++e) out[e] = siluf(acc[e]);
; }
; DI float softplusf(float x) { return x > 20.f ? x : log1pf(__expf(x)); }
; DI float wave_incl_scan(float v) {
;   const int lane = get_tid() & 63;
;   for (int o = 1; o < 64; o <<= 1) { float u = __shfl_up(v, o); if (lane >= o) v += u; }
;   return v;
; }
; DI void phase_ssdconv(PP p, int l) {
;   const u16* zx = (const u16*)(p->ws + A_SSDZX);
;   u16* xs = (u16*)(p->ws + A_XSACT); u16* bc = (u16*)(p->ws + A_BCACT);
;   const float* cw = p->in[I_SCW] + (size_t)l * 5 * 1024; const float* cb = p->in[I_SCB] + l * 1024;
;   const int total = ROWS * 128;
;   for (int i = get_bid() * 256 + get_tid(); i < total; i += gridDim.x * 256) {
;     const int row = i >> 7, ch0 = (i & 127) * 8;
;     const int b = row / TT, t = row - b * TT;
;     const int lo = t < CTX ? b * TT : b * TT + CTX, hi = t < CTX ? b * TT + CTX : (b + 1) * TT;
;     float v[8];
;     ssd_conv8(zx, row, lo, hi, ch0, cw, cb, v);
;     u16* dst = ch0 < 512 ? xs + (size_t)row * 512 + ch0 : bc + (size_t)row * 512 + (ch0 - 512);
;     *(U4*)dst = pack8(v);
.LBB0_583:
	s_andn2_b64 vcc, exec, s[0:1]
	s_cbranch_vccnz .LBB0_602
	v_lshrrev_b32_e32 v0, 6, v163
	v_readlane_b32 s2, v249, 0
	v_readfirstlane_b32 s3, v0
	v_and_b32_e32 v0, 0x7f, v163
	v_lshlrev_b32_e32 v2, 4, v0
	v_lshlrev_b32_e32 v173, 5, v0
	v_add_u32_e32 v2, 0x400, v2
	v_and_b32_e32 v0, 63, v163
	v_lshlrev_b32_e32 v3, 4, v0
	s_lshr_b32 s4, s3, 1
	s_lshl_b32 s0, s2, 1
	s_add_i32 s0, s0, s4
	v_readlane_b32 s14, v251, 35
	v_readlane_b32 s15, v251, 36
	v_readlane_b32 s5, v251, 31
	s_load_dwordx4 s[8:11], s[14:15], 0x68
	s_mul_i32 s6, s5, 0x5000
	s_lshl_b32 s7, s5, 12
	s_waitcnt lgkmcnt(0)
	s_add_u32 s8, s8, s6
	s_addc_u32 s9, s9, 0
	s_add_u32 s10, s10, s7
	s_addc_u32 s11, s11, 0
	global_load_dwordx4 v[176:179], v173, s[10:11]
	global_load_dwordx4 v[180:183], v173, s[10:11] offset:16
	global_load_dwordx4 v[118:121], v173, s[8:9]
	global_load_dwordx4 v[122:125], v173, s[8:9] offset:16
	v_add_u32_e32 v173, 0x1000, v173
	global_load_dwordx4 v[126:129], v173, s[8:9]
	global_load_dwordx4 v[130:133], v173, s[8:9] offset:16
	v_add_u32_e32 v173, 0x1000, v173
	global_load_dwordx4 v[134:137], v173, s[8:9]
	global_load_dwordx4 v[138:141], v173, s[8:9] offset:16
	v_add_u32_e32 v173, 0x1000, v173
	global_load_dwordx4 v[142:145], v173, s[8:9]
	global_load_dwordx4 v[146:149], v173, s[8:9] offset:16
	v_add_u32_e32 v173, 0x1000, v173
	global_load_dwordx4 v[150:153], v173, s[8:9]
	global_load_dwordx4 v[154:157], v173, s[8:9] offset:16
	s_waitcnt vmcnt(0)
	v_mov_b64_e32 v[158:159], v[176:177]
	v_mov_b64_e32 v[160:161], v[178:179]
	v_mov_b64_e32 v[166:167], v[180:181]
	v_mov_b64_e32 v[168:169], v[182:183]
	s_add_u32 s8, s48, 0x7b00000
	s_addc_u32 s9, s49, 0
	s_and_b32 s4, s3, 1
	s_cmp_eq_u32 s4, 1
	s_mov_b32 s5, 0x14100000
	s_mov_b32 s12, 0xff00000
	s_cselect_b32 s4, s5, s12
	s_add_u32 s10, s48, s4
	s_addc_u32 s11, s49, 0
	v_readlane_b32 s15, v251, 30
	s_nop 0
	s_lshr_b32 s15, s15, 7
	s_cmp_ge_u32 s0, 0x2100
	s_cselect_b32 s2, 1, 0
	s_cmp_ge_u32 s0, 0x4200
	s_addc_u32 s2, s2, 0
	s_cmp_ge_u32 s0, 0x6300
	s_addc_u32 s2, s2, 0
	s_mul_i32 s4, s2, 0x2100
	s_sub_i32 s3, s0, s4
	s_add_i32 s5, s4, 0x100
	s_add_i32 s12, s4, 0x2100
	s_cmp_lt_u32 s3, 0x100
	s_cselect_b32 s4, s4, s5
	s_cselect_b32 s5, s5, s12
	s_mov_b32 s7, 4
	s_add_i32 s12, s0, -2
	s_cmp_ge_i32 s12, s4
	s_cselect_b32 s13, 1, 0
	s_cmp_lt_i32 s12, s5
	s_cselect_b32 s13, s13, 0
	s_lshl_b32 s13, s13, 0
	s_or_b32 s7, s7, s13
	s_add_i32 s12, s0, -1
	s_cmp_ge_i32 s12, s4
	s_cselect_b32 s13, 1, 0
	s_cmp_lt_i32 s12, s5
	s_cselect_b32 s13, s13, 0
	s_lshl_b32 s13, s13, 1
	s_or_b32 s7, s7, s13
	s_add_i32 s12, s0, 1
	s_cmp_ge_i32 s12, s4
	s_cselect_b32 s13, 1, 0
	s_cmp_lt_i32 s12, s5
	s_cselect_b32 s13, s13, 0
	s_lshl_b32 s13, s13, 3
	s_or_b32 s7, s7, s13
	s_add_i32 s12, s0, 2
	s_cmp_ge_i32 s12, s4
	s_cselect_b32 s13, 1, 0
	s_cmp_lt_i32 s12, s5
	s_cselect_b32 s13, s13, 0
	s_lshl_b32 s13, s13, 4
	s_or_b32 s7, s7, s13
	s_add_i32 s12, s0, -2
	s_bitcmp1_b32 s7, 0
	s_cselect_b32 s12, s12, s0
	s_mul_i32 s12, s12, 0xc00
	v_add_u32_e32 v0, s12, v2
	global_load_dwordx4 v[4:7], v0, s[8:9]
	s_add_i32 s12, s0, -1
	s_bitcmp1_b32 s7, 1
	s_cselect_b32 s12, s12, s0
	s_mul_i32 s12, s12, 0xc00
	v_add_u32_e32 v0, s12, v2
	global_load_dwordx4 v[8:11], v0, s[8:9]
	s_mul_i32 s12, s0, 0xc00
	v_add_u32_e32 v0, s12, v2
	global_load_dwordx4 v[12:15], v0, s[8:9]
	s_add_i32 s12, s0, 1
	s_bitcmp1_b32 s7, 3
	s_cselect_b32 s12, s12, s0
	s_mul_i32 s12, s12, 0xc00
	v_add_u32_e32 v0, s12, v2
	global_load_dwordx4 v[16:19], v0, s[8:9]
	s_add_i32 s12, s0, 2
	s_bitcmp1_b32 s7, 4
	s_cselect_b32 s12, s12, s0
	s_mul_i32 s12, s12, 0xc00
	v_add_u32_e32 v0, s12, v2
	global_load_dwordx4 v[20:23], v0, s[8:9]
	s_waitcnt vmcnt(0)
.Lsc_loop:
	v_mov_b64_e32 v[218:219], v[4:5]
	v_mov_b64_e32 v[220:221], v[6:7]
	v_mov_b64_e32 v[222:223], v[8:9]
	v_mov_b64_e32 v[224:225], v[10:11]
	v_mov_b64_e32 v[226:227], v[12:13]
	v_mov_b64_e32 v[228:229], v[14:15]
	v_mov_b64_e32 v[230:231], v[16:17]
	v_mov_b64_e32 v[232:233], v[18:19]
	v_mov_b64_e32 v[234:235], v[20:21]
	v_mov_b64_e32 v[236:237], v[22:23]
	s_mov_b32 s6, s7
	s_add_i32 s1, s0, s15
	s_cmp_ge_u32 s1, 0x8400
	s_cselect_b32 s14, 1, 0
	s_cselect_b32 s1, s0, s1
	s_cmp_ge_u32 s1, 0x2100
	s_cselect_b32 s2, 1, 0
	s_cmp_ge_u32 s1, 0x4200
	s_addc_u32 s2, s2, 0
	s_cmp_ge_u32 s1, 0x6300
	s_addc_u32 s2, s2, 0
	s_mul_i32 s4, s2, 0x2100
	s_sub_i32 s3, s1, s4
	s_add_i32 s5, s4, 0x100
	s_add_i32 s12, s4, 0x2100
	s_cmp_lt_u32 s3, 0x100
	s_cselect_b32 s4, s4, s5
	s_cselect_b32 s5, s5, s12
	s_mov_b32 s7, 4
	s_add_i32 s12, s1, -2
	s_cmp_ge_i32 s12, s4
	s_cselect_b32 s13, 1, 0
	s_cmp_lt_i32 s12, s5
	s_cselect_b32 s13, s13, 0
	s_lshl_b32 s13, s13, 0
	s_or_b32 s7, s7, s13
	s_add_i32 s12, s1, -1
	s_cmp_ge_i32 s12, s4
	s_cselect_b32 s13, 1, 0
	s_cmp_lt_i32 s12, s5
	s_cselect_b32 s13, s13, 0
	s_lshl_b32 s13, s13, 1
	s_or_b32 s7, s7, s13
	s_add_i32 s12, s1, 1
	s_cmp_ge_i32 s12, s4
	s_cselect_b32 s13, 1, 0
	s_cmp_lt_i32 s12, s5
	s_cselect_b32 s13, s13, 0
	s_lshl_b32 s13, s13, 3
	s_or_b32 s7, s7, s13
	s_add_i32 s12, s1, 2
	s_cmp_ge_i32 s12, s4
	s_cselect_b32 s13, 1, 0
	s_cmp_lt_i32 s12, s5
	s_cselect_b32 s13, s13, 0
	s_lshl_b32 s13, s13, 4
	s_or_b32 s7, s7, s13
	s_add_i32 s12, s1, -2
	s_bitcmp1_b32 s7, 0
	s_cselect_b32 s12, s12, s1
	s_mul_i32 s12, s12, 0xc00
	v_add_u32_e32 v0, s12, v2
	global_load_dwordx4 v[4:7], v0, s[8:9]
	s_add_i32 s12, s1, -1
	s_bitcmp1_b32 s7, 1
	s_cselect_b32 s12, s12, s1
	s_mul_i32 s12, s12, 0xc00
	v_add_u32_e32 v0, s12, v2
	global_load_dwordx4 v[8:11], v0, s[8:9]
	s_mul_i32 s12, s1, 0xc00
	v_add_u32_e32 v0, s12, v2
	global_load_dwordx4 v[12:15], v0, s[8:9]
	s_add_i32 s12, s1, 1
	s_bitcmp1_b32 s7, 3
	s_cselect_b32 s12, s12, s1
	s_mul_i32 s12, s12, 0xc00
	v_add_u32_e32 v0, s12, v2
	global_load_dwordx4 v[16:19], v0, s[8:9]
	s_add_i32 s12, s1, 2
	s_bitcmp1_b32 s7, 4
	s_cselect_b32 s12, s12, s1
	s_mul_i32 s12, s12, 0xc00
	v_add_u32_e32 v0, s12, v2
	global_load_dwordx4 v[20:23], v0, s[8:9]
	v_mov_b64_e32 v[24:25], v[158:159]
	v_mov_b64_e32 v[26:27], v[160:161]
	v_mov_b64_e32 v[28:29], v[166:167]
	v_mov_b64_e32 v[30:31], v[168:169]
	s_bitcmp1_b32 s6, 0
	s_cbranch_scc0 .Lsc_skip0
	v_lshlrev_b32_e32 v188, 16, v218
	v_and_b32_e32 v189, 0xffff0000, v218
	v_lshlrev_b32_e32 v190, 16, v219
	v_and_b32_e32 v191, 0xffff0000, v219
	v_lshlrev_b32_e32 v192, 16, v220
	v_and_b32_e32 v193, 0xffff0000, v220
	v_lshlrev_b32_e32 v194, 16, v221
	v_and_b32_e32 v195, 0xffff0000, v221
	v_pk_fma_f32 v[24:25], v[118:119], v[188:189], v[24:25]
	v_pk_fma_f32 v[26:27], v[120:121], v[190:191], v[26:27]
	v_pk_fma_f32 v[28:29], v[122:123], v[192:193], v[28:29]
	v_pk_fma_f32 v[30:31], v[124:125], v[194:195], v[30:31]
; DI U4 pack8(const float (&x)[8]) { return mku4(pack2(x[0], x[1]), pack2(x[2], x[3]), pack2(x[4], x[5]), pack2(x[6], x[7])); }
; DI float siluf(float x) { return x / (1.f + __expf(-x)); }
; DI void ssd_conv8(const u16* zx, int row, int lo, int hi, int ch0, const float* cw, const float* cb, float (&out)[8]) {
;     ...
;   for (int k = 0; k < 5; ++k) {
;     int rr = row + k - 2;
;     if (rr >= lo && rr < hi) {
;       U4 v = *(const U4*)(zx + (size_t)rr * 1536 + 512 + ch0); float x[8]; unpack8(v, x);
;       F4 w0 = *(const F4*)(cw + k * 1024 + ch0), w1 = *(const F4*)(cw + k * 1024 + ch0 + 4);
;       acc[0] += w0.x * x[0]; acc[1] += w0.y * x[1]; acc[2] += w0.z * x[2]; acc[3] += w0.w * x[3];
;       acc[4] += w1.x * x[4]; acc[5] += w1.y * x[5]; acc[6] += w1.z * x[6]; acc[7] += w1.w * x[7];
;     }
;   }
; #pragma unroll
;   for (int e = 0; e < 8; ++e) out[e] = siluf(acc[e]);
; DI void phase_ssdconv(PP p, int l) {
;     ...
;     ssd_conv8(zx, row, lo, hi, ch0, cw, cb, v);
;     u16* dst = ch0 < 512 ? xs + (size_t)row * 512 + ch0 : bc + (size_t)row * 512 + (ch0 - 512);
;     *(U4*)dst = pack8(v);
.Lsc_skip0:
	s_bitcmp1_b32 s6, 1
	s_cbranch_scc0 .Lsc_skip1
	v_lshlrev_b32_e32 v188, 16, v222
	v_and_b32_e32 v189, 0xffff0000, v222
	v_lshlrev_b32_e32 v190, 16, v223
	v_and_b32_e32 v191, 0xffff0000, v223
	v_lshlrev_b32_e32 v192, 16, v224
	v_and_b32_e32 v193, 0xffff0000, v224
	v_lshlrev_b32_e32 v194, 16, v225
	v_and_b32_e32 v195, 0xffff0000, v225
	v_pk_fma_f32 v[24:25], v[126:127], v[188:189], v[24:25]
	v_pk_fma_f32 v[26:27], v[128:129], v[190:191], v[26:27]
	v_pk_fma_f32 v[28:29], v[130:131], v[192:193], v[28:29]
	v_pk_fma_f32 v[30:31], v[132:133], v[194:195], v[30:31]
.Lsc_skip1:
	v_lshlrev_b32_e32 v188, 16, v226
	v_and_b32_e32 v189, 0xffff0000, v226
	v_lshlrev_b32_e32 v190, 16, v227
	v_and_b32_e32 v191, 0xffff0000, v227
	v_lshlrev_b32_e32 v192, 16, v228
	v_and_b32_e32 v193, 0xffff0000, v228
	v_lshlrev_b32_e32 v194, 16, v229
	v_and_b32_e32 v195, 0xffff0000, v229
	v_pk_fma_f32 v[24:25], v[134:135], v[188:189], v[24:25]
	v_pk_fma_f32 v[26:27], v[136:137], v[190:191], v[26:27]
	v_pk_fma_f32 v[28:29], v[138:139], v[192:193], v[28:29]
	v_pk_fma_f32 v[30:31], v[140:141], v[194:195], v[30:31]
	s_bitcmp1_b32 s6, 3
	s_cbranch_scc0 .Lsc_skip3
	v_lshlrev_b32_e32 v188, 16, v230
	v_and_b32_e32 v189, 0xffff0000, v230
	v_lshlrev_b32_e32 v190, 16, v231
	v_and_b32_e32 v191, 0xffff0000, v231
	v_lshlrev_b32_e32 v192, 16, v232
	v_and_b32_e32 v193, 0xffff0000, v232
	v_lshlrev_b32_e32 v194, 16, v233
	v_and_b32_e32 v195, 0xffff0000, v233
	v_pk_fma_f32 v[24:25], v[142:143], v[188:189], v[24:25]
	v_pk_fma_f32 v[26:27], v[144:145], v[190:191], v[26:27]
	v_pk_fma_f32 v[28:29], v[146:147], v[192:193], v[28:29]
	v_pk_fma_f32 v[30:31], v[148:149], v[194:195], v[30:31]
.Lsc_skip3:
	s_bitcmp1_b32 s6, 4
	s_cbranch_scc0 .Lsc_skip4
	v_lshlrev_b32_e32 v188, 16, v234
	v_and_b32_e32 v189, 0xffff0000, v234
	v_lshlrev_b32_e32 v190, 16, v235
	v_and_b32_e32 v191, 0xffff0000, v235
	v_lshlrev_b32_e32 v192, 16, v236
	v_and_b32_e32 v193, 0xffff0000, v236
	v_lshlrev_b32_e32 v194, 16, v237
	v_and_b32_e32 v195, 0xffff0000, v237
	v_pk_fma_f32 v[24:25], v[150:151], v[188:189], v[24:25]
	v_pk_fma_f32 v[26:27], v[152:153], v[190:191], v[26:27]
	v_pk_fma_f32 v[28:29], v[154:155], v[192:193], v[28:29]
	v_pk_fma_f32 v[30:31], v[156:157], v[194:195], v[30:31]
.Lsc_skip4:
	v_mul_f32_e32 v174, 0xbfb8aa3b, v24
	v_mul_f32_e32 v175, 0xbfb8aa3b, v25
	v_exp_f32_e32 v174, v174
	v_exp_f32_e32 v175, v175
	s_nop 0
	v_pk_add_f32 v[174:175], v[174:175], 1.0 op_sel_hi:[1,0]
	s_nop 0
	v_div_scale_f32 v196, s[12:13], v174, v174, v24
	v_rcp_f32_e32 v197, v196
	s_nop 0
	v_fma_f32 v170, -v196, v197, 1.0
	v_fmac_f32_e32 v197, v170, v197
	v_div_scale_f32 v171, vcc, v24, v174, v24
	v_mul_f32_e32 v172, v171, v197
	v_fma_f32 v170, -v196, v172, v171
	v_fmac_f32_e32 v172, v170, v197
	v_fma_f32 v196, -v196, v172, v171
	v_div_fmas_f32 v196, v196, v197, v172
	v_div_fixup_f32 v176, v196, v174, v24
	v_div_scale_f32 v196, s[12:13], v175, v175, v25
	v_rcp_f32_e32 v197, v196
	s_nop 0
	v_fma_f32 v170, -v196, v197, 1.0
	v_fmac_f32_e32 v197, v170, v197
	v_div_scale_f32 v171, vcc, v25, v175, v25
	v_mul_f32_e32 v172, v171, v197
	v_fma_f32 v170, -v196, v172, v171
	v_fmac_f32_e32 v172, v170, v197
	v_fma_f32 v196, -v196, v172, v171
	v_div_fmas_f32 v196, v196, v197, v172
	v_div_fixup_f32 v177, v196, v175, v25
	v_mul_f32_e32 v174, 0xbfb8aa3b, v26
	v_mul_f32_e32 v175, 0xbfb8aa3b, v27
	v_exp_f32_e32 v174, v174
	v_exp_f32_e32 v175, v175
	s_nop 0
	v_pk_add_f32 v[174:175], v[174:175], 1.0 op_sel_hi:[1,0]
	s_nop 0
	v_div_scale_f32 v196, s[12:13], v174, v174, v26
	v_rcp_f32_e32 v197, v196
	s_nop 0
	v_fma_f32 v170, -v196, v197, 1.0
	v_fmac_f32_e32 v197, v170, v197
	v_div_scale_f32 v171, vcc, v26, v174, v26
	v_mul_f32_e32 v172, v171, v197
	v_fma_f32 v170, -v196, v172, v171
	v_fmac_f32_e32 v172, v170, v197
	v_fma_f32 v196, -v196, v172, v171
	v_div_fmas_f32 v196, v196, v197, v172
	v_div_fixup_f32 v178, v196, v174, v26
	v_div_scale_f32 v196, s[12:13], v175, v175, v27
	v_rcp_f32_e32 v197, v196
	s_nop 0
	v_fma_f32 v170, -v196, v197, 1.0
	v_fmac_f32_e32 v197, v170, v197
	v_div_scale_f32 v171, vcc, v27, v175, v27
	v_mul_f32_e32 v172, v171, v197
	v_fma_f32 v170, -v196, v172, v171
	v_fmac_f32_e32 v172, v170, v197
	v_fma_f32 v196, -v196, v172, v171
	v_div_fmas_f32 v196, v196, v197, v172
	v_div_fixup_f32 v179, v196, v175, v27
	v_mul_f32_e32 v174, 0xbfb8aa3b, v28
	v_mul_f32_e32 v175, 0xbfb8aa3b, v29
	v_exp_f32_e32 v174, v174
	v_exp_f32_e32 v175, v175
	s_nop 0
	v_pk_add_f32 v[174:175], v[174:175], 1.0 op_sel_hi:[1,0]
	s_nop 0
	v_div_scale_f32 v196, s[12:13], v174, v174, v28
	v_rcp_f32_e32 v197, v196
	s_nop 0
	v_fma_f32 v170, -v196, v197, 1.0
	v_fmac_f32_e32 v197, v170, v197
	v_div_scale_f32 v171, vcc, v28, v174, v28
	v_mul_f32_e32 v172, v171, v197
	v_fma_f32 v170, -v196, v172, v171
	v_fmac_f32_e32 v172, v170, v197
	v_fma_f32 v196, -v196, v172, v171
	v_div_fmas_f32 v196, v196, v197, v172
	v_div_fixup_f32 v180, v196, v174, v28
	v_div_scale_f32 v196, s[12:13], v175, v175, v29
	v_rcp_f32_e32 v197, v196
	s_nop 0
	v_fma_f32 v170, -v196, v197, 1.0
	v_fmac_f32_e32 v197, v170, v197
	v_div_scale_f32 v171, vcc, v29, v175, v29
	v_mul_f32_e32 v172, v171, v197
	v_fma_f32 v170, -v196, v172, v171
	v_fmac_f32_e32 v172, v170, v197
	v_fma_f32 v196, -v196, v172, v171
	v_div_fmas_f32 v196, v196, v197, v172
	v_div_fixup_f32 v181, v196, v175, v29
	v_mul_f32_e32 v174, 0xbfb8aa3b, v30
	v_mul_f32_e32 v175, 0xbfb8aa3b, v31
	v_exp_f32_e32 v174, v174
	v_exp_f32_e32 v175, v175
	s_nop 0
	v_pk_add_f32 v[174:175], v[174:175], 1.0 op_sel_hi:[1,0]
	s_nop 0
	v_div_scale_f32 v196, s[12:13], v174, v174, v30
	v_rcp_f32_e32 v197, v196
	s_nop 0
	v_fma_f32 v170, -v196, v197, 1.0
	v_fmac_f32_e32 v197, v170, v197
	v_div_scale_f32 v171, vcc, v30, v174, v30
	v_mul_f32_e32 v172, v171, v197
	v_fma_f32 v170, -v196, v172, v171
	v_fmac_f32_e32 v172, v170, v197
	v_fma_f32 v196, -v196, v172, v171
	v_div_fmas_f32 v196, v196, v197, v172
	v_div_fixup_f32 v182, v196, v174, v30
	v_div_scale_f32 v196, s[12:13], v175, v175, v31
	v_rcp_f32_e32 v197, v196
	s_nop 0
	v_fma_f32 v170, -v196, v197, 1.0
	v_fmac_f32_e32 v197, v170, v197
	v_div_scale_f32 v171, vcc, v31, v175, v31
	v_mul_f32_e32 v172, v171, v197
	v_fma_f32 v170, -v196, v172, v171
	v_fmac_f32_e32 v172, v170, v197
	v_fma_f32 v196, -v196, v172, v171
	v_div_fmas_f32 v196, v196, v197, v172
	v_div_fixup_f32 v183, v196, v175, v31
	v_cvt_pk_bf16_f32 v188, v176, v177
	v_cvt_pk_bf16_f32 v189, v178, v179
	v_cvt_pk_bf16_f32 v190, v180, v181
	v_cvt_pk_bf16_f32 v191, v182, v183
	s_lshl_b32 s12, s0, 10
	v_add_u32_e32 v0, s12, v3
	global_store_dwordx4 v0, v[188:191], s[10:11]
	s_waitcnt vmcnt(1)
	s_cmp_eq_u32 s14, 1
	s_cbranch_scc1 .Lsc_done
	s_mov_b32 s0, s1
	s_branch .Lsc_loop
.Lsc_done:
	s_waitcnt vmcnt(0)
.LBB0_601:
	s_or_b64 exec, exec, s[2:3]
